# full stack: K-blocked inproj+outproj operands, merge K-loop load hoisting, L1-bypass inproj loads, compact index keys, coalesced attention key gathers
# speedup vs baseline: 1.0173x; 1.0173x over previous
; template <int NI, class LA, class LB, class EP>
; __device__ __forceinline__ void gemm_tile(int K, LA loadA, LB loadB, EP epi, char* smem) {
;     ...
;   for (int kt = 0; kt < nk; ++kt) {
;     __syncthreads();
; #pragma unroll
;     for (int i = 0; i < 4; ++i) *(uint4*)&sA[(lr + 32 * i) * 72 + lc] = ra[i];
; #pragma unroll
;     for (int i = 0; i < NB; ++i) *(uint4*)&sB[(lr + 32 * i) * 72 + lc] = rb[i];
;     __syncthreads();
;     if (kt + 1 < nk) {
;       const int kk = (kt + 1) * 64 + lc;
; #pragma unroll
;       for (int i = 0; i < 4; ++i) ra[i] = loadA(lr + 32 * i, kk);
; #pragma unroll
;       for (int i = 0; i < NB; ++i) rb[i] = loadB(lr + 32 * i, kk);
;     }
; #pragma unroll
;     for (int s = 0; s < 4; ++s) {
;       h8 af[2], bf[NI];
; #pragma unroll
;       for (int mi = 0; mi < 2; ++mi)
;         af[mi] = *(const h8*)&sA[(wm * 64 + mi * 32 + (lane & 31)) * 72 + s * 16 + (lane >> 5) * 8];
; #pragma unroll
;       for (int ni = 0; ni < NI; ++ni)
;         bf[ni] = *(const h8*)&sB[(wn * (NI * 32) + ni * 32 + (lane & 31)) * 72 + s * 16 + (lane >> 5) * 8];
; #pragma unroll
;       for (int mi = 0; mi < 2; ++mi)
; #pragma unroll
;         for (int ni = 0; ni < NI; ++ni)
;           acc[mi][ni] = __builtin_amdgcn_mfma_f32_32x32x16_f16(af[mi], bf[ni], acc[mi][ni], 0, 0, 0);
;     }
; __device__ __forceinline__ void phase_merge(const KP& p, char* smem, int* q, int xcc) {
;     ...
;       gemm_tile<2>(
;           512, [&](int r, int k) { return *(const uint4*)(A + (size_t)r * 512 + k); },
.LBB0_1743:
	s_waitcnt vmcnt(63) expcnt(7) lgkmcnt(15)
	s_barrier
	s_waitcnt vmcnt(7)
	ds_write_b128 v172, v[192:195]
	s_waitcnt vmcnt(6)
	ds_write_b128 v172, v[196:199] offset:4608
	s_waitcnt vmcnt(5)
	ds_write_b128 v172, v[200:203] offset:9216
	s_waitcnt vmcnt(4)
	ds_write_b128 v172, v[204:207] offset:13824
	s_waitcnt vmcnt(3)
	ds_write_b128 v172, v[208:211] offset:18432
	s_waitcnt vmcnt(2)
	ds_write_b128 v172, v[212:215] offset:23040
	s_waitcnt vmcnt(1)
	ds_write_b128 v172, v[216:219] offset:27648
	s_waitcnt vmcnt(0)
	ds_write_b128 v172, v[220:223] offset:32256
	global_load_dwordx4 v[192:195], v[228:229], off
	global_load_dwordx4 v[196:199], v[230:231], off
	global_load_dwordx4 v[200:203], v[232:233], off
	global_load_dwordx4 v[204:207], v[234:235], off
	global_load_dwordx4 v[208:211], v[238:239], off
	global_load_dwordx4 v[212:215], v[240:241], off
	global_load_dwordx4 v[216:219], v[242:243], off
	global_load_dwordx4 v[220:223], v[244:245], off
	s_waitcnt lgkmcnt(0)
	s_barrier
	ds_read_b128 v[66:69], v162
	ds_read_b128 v[70:73], v163 offset:18432
	ds_read_b128 v[74:77], v162 offset:32
	ds_read_b128 v[78:81], v163 offset:18464
	ds_read_b128 v[82:85], v171 offset:18432
	ds_read_b128 v[174:177], v163 offset:23136
	s_waitcnt lgkmcnt(4)
	v_mfma_f32_32x32x16_f16 v[50:65], v[66:69], v[70:73], v[50:65]
	s_waitcnt lgkmcnt(1)
	v_mfma_f32_32x32x16_f16 v[34:49], v[66:69], v[82:85], v[34:49]
	v_lshl_add_u64 v[228:229], v[228:229], 0, s[2:3]
	ds_read_b128 v[66:69], v162 offset:4608
	ds_read_b128 v[86:89], v162 offset:4640
	s_waitcnt lgkmcnt(1)
	v_mfma_f32_32x32x16_f16 v[18:33], v[66:69], v[70:73], v[18:33]
	v_mfma_f32_32x32x16_f16 v[2:17], v[66:69], v[82:85], v[2:17]
	v_lshl_add_u64 v[230:231], v[230:231], 0, s[2:3]
	ds_read_b128 v[66:69], v163 offset:23072
	ds_read_b128 v[70:73], v163 offset:23104
	v_mfma_f32_32x32x16_f16 v[50:65], v[74:77], v[78:81], v[50:65]
	s_waitcnt lgkmcnt(1)
	v_mfma_f32_32x32x16_f16 v[34:49], v[74:77], v[66:69], v[34:49]
	v_lshl_add_u64 v[232:233], v[232:233], 0, s[2:3]
	v_mfma_f32_32x32x16_f16 v[18:33], v[86:89], v[78:81], v[18:33]
	v_mfma_f32_32x32x16_f16 v[2:17], v[86:89], v[66:69], v[2:17]
	v_lshl_add_u64 v[234:235], v[234:235], 0, s[2:3]
	ds_read_b128 v[66:69], v162 offset:64
	ds_read_b128 v[74:77], v163 offset:18496
	ds_read_b128 v[78:81], v162 offset:96
	ds_read_b128 v[82:85], v163 offset:18528
	ds_read_b128 v[86:89], v162 offset:4672
	ds_read_b128 v[178:181], v162 offset:4704
	s_waitcnt lgkmcnt(4)
	v_mfma_f32_32x32x16_f16 v[50:65], v[66:69], v[74:77], v[50:65]
	v_mfma_f32_32x32x16_f16 v[34:49], v[66:69], v[70:73], v[34:49]
	v_lshl_add_u64 v[238:239], v[238:239], 0, s[2:3]
	s_waitcnt lgkmcnt(1)
	v_mfma_f32_32x32x16_f16 v[18:33], v[86:89], v[74:77], v[18:33]
	v_mfma_f32_32x32x16_f16 v[2:17], v[86:89], v[70:73], v[2:17]
	v_lshl_add_u64 v[240:241], v[240:241], 0, s[2:3]
	v_mfma_f32_32x32x16_f16 v[50:65], v[78:81], v[82:85], v[50:65]
	v_mfma_f32_32x32x16_f16 v[34:49], v[78:81], v[174:177], v[34:49]
	v_lshl_add_u64 v[242:243], v[242:243], 0, s[2:3]
	s_waitcnt lgkmcnt(0)
	v_mfma_f32_32x32x16_f16 v[18:33], v[178:181], v[82:85], v[18:33]
	v_mfma_f32_32x32x16_f16 v[2:17], v[178:181], v[174:177], v[2:17]
	v_lshl_add_u64 v[244:245], v[244:245], 0, s[2:3]
	s_add_u32 s40, s40, 0x80
	s_addc_u32 s41, s41, 0
	s_cmpk_lg_i32 s40, 0x380
	s_cbranch_scc1 .LBB0_1743
	s_barrier
	s_waitcnt vmcnt(7)
	ds_write_b128 v172, v[192:195]
	s_waitcnt vmcnt(6)
	ds_write_b128 v172, v[196:199] offset:4608
	s_waitcnt vmcnt(5)
	ds_write_b128 v172, v[200:203] offset:9216
	s_waitcnt vmcnt(4)
	ds_write_b128 v172, v[204:207] offset:13824
	s_waitcnt vmcnt(3)
	ds_write_b128 v172, v[208:211] offset:18432
	s_waitcnt vmcnt(2)
	ds_write_b128 v172, v[212:215] offset:23040
	s_waitcnt vmcnt(1)
	ds_write_b128 v172, v[216:219] offset:27648
	s_waitcnt vmcnt(0)
	ds_write_b128 v172, v[220:223] offset:32256
	s_waitcnt lgkmcnt(0)
	s_barrier
	ds_read_b128 v[66:69], v162 offset:4608
	ds_read_b128 v[70:73], v171 offset:18432
	ds_read_b128 v[74:77], v162
	ds_read_b128 v[78:81], v162 offset:32
	ds_read_b128 v[82:85], v163 offset:18432
	ds_read_b128 v[86:89], v163 offset:18464
	s_waitcnt lgkmcnt(1)
	v_mfma_f32_32x32x16_f16 v[50:65], v[74:77], v[82:85], v[50:65]
	s_lshl_b32 s2, s56, 11
	s_add_u32 s2, s52, s2
	s_addc_u32 s3, s53, 0
	v_lshlrev_b32_e32 v0, 1, v0
	s_add_i32 s56, s56, 1
	s_add_u32 s38, s38, 0x100000
	s_addc_u32 s39, s39, 0
	v_mfma_f32_32x32x16_f16 v[34:49], v[74:77], v[70:73], v[34:49]
	s_cmp_lg_u32 s56, 3
	v_mfma_f32_32x32x16_f16 v[18:33], v[66:69], v[82:85], v[18:33]
	v_mfma_f32_32x32x16_f16 v[2:17], v[66:69], v[70:73], v[2:17]
	ds_read_b128 v[66:69], v162 offset:4640
	ds_read_b128 v[70:73], v163 offset:23072
	s_waitcnt lgkmcnt(2)
	v_mfma_f32_32x32x16_f16 v[50:65], v[78:81], v[86:89], v[50:65]
	s_waitcnt lgkmcnt(0)
	v_mfma_f32_32x32x16_f16 v[34:49], v[78:81], v[70:73], v[34:49]
	v_mfma_f32_32x32x16_f16 v[18:33], v[66:69], v[86:89], v[18:33]
	v_mfma_f32_32x32x16_f16 v[2:17], v[66:69], v[70:73], v[2:17]
	ds_read_b128 v[66:69], v162 offset:64
	ds_read_b128 v[70:73], v162 offset:4672
	ds_read_b128 v[74:77], v163 offset:18496
	ds_read_b128 v[78:81], v163 offset:23104
	s_waitcnt lgkmcnt(1)
	v_mfma_f32_32x32x16_f16 v[50:65], v[66:69], v[74:77], v[50:65]
	s_waitcnt lgkmcnt(0)
	v_mfma_f32_32x32x16_f16 v[34:49], v[66:69], v[78:81], v[34:49]
	v_mfma_f32_32x32x16_f16 v[18:33], v[70:73], v[74:77], v[18:33]
	v_mfma_f32_32x32x16_f16 v[2:17], v[70:73], v[78:81], v[2:17]
	ds_read_b128 v[66:69], v162 offset:96
	ds_read_b128 v[70:73], v162 offset:4704
	ds_read_b128 v[74:77], v163 offset:18528
	ds_read_b128 v[78:81], v163 offset:23136
	s_waitcnt lgkmcnt(1)
;   __device__ __forceinline__ const float* x() const { return (const float*)(const __attribute__((address_space(1))) float*)kp[0]; }
; __device__ __forceinline__ float sigmoidf_(float x) { return 1.f / (1.f + __expf(-x)); }
; __device__ __forceinline__ void phase_merge(const KP& p, char* smem, int* q, int xcc) {
;     ...
;           [&](int mi, int ni, int r, int row, int col, float v) {
;             const float gz = (float)G[(size_t)row * NU + col];
;             tot[mi][ni][r] += sigmoidf_(gz) * v;
;           },
	v_mfma_f32_32x32x16_f16 v[50:65], v[66:69], v[74:77], v[50:65]
	s_waitcnt lgkmcnt(0)
	v_mfma_f32_32x32x16_f16 v[34:49], v[66:69], v[78:81], v[34:49]
	v_mfma_f32_32x32x16_f16 v[18:33], v[70:73], v[74:77], v[18:33]
	v_mfma_f32_32x32x16_f16 v[2:17], v[70:73], v[78:81], v[2:17]
	v_mov_b32_e32 v228, 0x11fe4
	v_mov_b32_e32 v229, 0x100
	v_mov_b32_e32 v230, 2
	v_mov_b32_e32 v231, 0x3727c5ac
	v_mov_b32_e32 v232, 0x11fa0
	v_mov_b32_e32 v233, 0x80000
	v_mov_b32_e32 v234, 0x1d0000
	v_mov_b32_e32 v235, 0xa800
	v_mov_b32_e32 v238, 0x4000
	v_mov_b32_e32 v239, 0x4400
	v_mov_b32_e32 v240, 0x4800
	v_mov_b32_e32 v241, 0x4c00
	v_mov_b32_e32 v242, 0xf149f2ca
	v_mov_b32_e32 v243, 0x200
	v_mov_b32_e32 v244, 0x400
	v_mov_b32_e32 v245, 0x600
	v_lshrrev_b32_e32 v94, 7, v224
	v_lshlrev_b32_e32 v94, 4, v94
	v_bfe_u32 v95, v224, 5, 1
	v_add_u32_e32 v94, v94, v95
	v_mul_u32_u24_e32 v94, 0xe800, v94
	v_bfe_u32 v95, v224, 6, 1
	v_lshl_add_u32 v94, v95, 7, v94
	v_and_b32_e32 v95, 31, v224
	v_lshl_add_u32 v94, v95, 1, v94
	s_mov_b64 s[40:41], s[2:3]
	v_mov_b32_e32 v96, v94
	global_load_ushort v192, v96, s[40:41]
	v_add_u32_e32 v96, 0x3a00, v94
	global_load_ushort v193, v96, s[40:41]
	v_add_u32_e32 v96, 0x7400, v94
	global_load_ushort v194, v96, s[40:41]
	v_add_u32_e32 v96, 0xae00, v94
	global_load_ushort v195, v96, s[40:41]
	v_add_u32_e32 v96, 0x1d000, v94
	global_load_ushort v196, v96, s[40:41]
	v_add_u32_e32 v96, 0x20a00, v94
	global_load_ushort v197, v96, s[40:41]
	v_add_u32_e32 v96, 0x24400, v94
	global_load_ushort v198, v96, s[40:41]
	v_add_u32_e32 v96, 0x27e00, v94
	global_load_ushort v199, v96, s[40:41]
	v_add_u32_e32 v96, 0x3a000, v94
	global_load_ushort v200, v96, s[40:41]
	v_add_u32_e32 v96, 0x3da00, v94
	global_load_ushort v201, v96, s[40:41]
	v_add_u32_e32 v96, 0x41400, v94
	global_load_ushort v202, v96, s[40:41]
	v_add_u32_e32 v96, 0x44e00, v94
	global_load_ushort v203, v96, s[40:41]
	v_add_u32_e32 v96, 0x57000, v94
	global_load_ushort v204, v96, s[40:41]
	v_add_u32_e32 v96, 0x5aa00, v94
	global_load_ushort v205, v96, s[40:41]
	v_add_u32_e32 v96, 0x5e400, v94
	global_load_ushort v206, v96, s[40:41]
	v_add_u32_e32 v96, 0x61e00, v94
	global_load_ushort v207, v96, s[40:41]
	v_mov_b32_e32 v96, v94
	global_load_ushort v208, v96, s[40:41] offset:64
	v_add_u32_e32 v96, 0x3a00, v94
	global_load_ushort v209, v96, s[40:41] offset:64
	v_add_u32_e32 v96, 0x7400, v94
	global_load_ushort v210, v96, s[40:41] offset:64
	v_add_u32_e32 v96, 0xae00, v94
	global_load_ushort v211, v96, s[40:41] offset:64
	v_add_u32_e32 v96, 0x1d000, v94
	global_load_ushort v212, v96, s[40:41] offset:64
	v_add_u32_e32 v96, 0x20a00, v94
	global_load_ushort v213, v96, s[40:41] offset:64
	v_add_u32_e32 v96, 0x24400, v94
	global_load_ushort v214, v96, s[40:41] offset:64
	v_add_u32_e32 v96, 0x27e00, v94
	global_load_ushort v215, v96, s[40:41] offset:64
	v_add_u32_e32 v96, 0x3a000, v94
	global_load_ushort v216, v96, s[40:41] offset:64
	v_add_u32_e32 v96, 0x3da00, v94
	global_load_ushort v217, v96, s[40:41] offset:64
	v_add_u32_e32 v96, 0x41400, v94
	global_load_ushort v218, v96, s[40:41] offset:64
	v_add_u32_e32 v96, 0x44e00, v94
	global_load_ushort v219, v96, s[40:41] offset:64
	v_add_u32_e32 v96, 0x57000, v94
	global_load_ushort v220, v96, s[40:41] offset:64
	v_add_u32_e32 v96, 0x5aa00, v94
	global_load_ushort v221, v96, s[40:41] offset:64
	v_add_u32_e32 v96, 0x5e400, v94
	global_load_ushort v222, v96, s[40:41] offset:64
	v_add_u32_e32 v96, 0x61e00, v94
	global_load_ushort v223, v96, s[40:41] offset:64
	s_nop 7
	s_waitcnt vmcnt(30)
	v_cvt_f32_f16_e32 v68, v192
	v_cvt_f32_f16_e32 v69, v193
	v_add_u32_e32 v96, 0x74000, v94
	global_load_ushort v192, v96, s[40:41]
	v_add_u32_e32 v96, 0x77a00, v94
	global_load_ushort v193, v96, s[40:41]
	v_mul_f32_e32 v68, 0xbfb8aa3b, v68
	v_mul_f32_e32 v69, 0xbfb8aa3b, v69
	v_exp_f32_e32 v68, v68
	v_exp_f32_e32 v69, v69
	s_nop 0
	v_pk_add_f32 v[68:69], v[68:69], 1.0 op_sel_hi:[1,0]
	s_nop 0
	v_div_scale_f32 v70, s[2:3], v69, v69, 1.0
	v_rcp_f32_e32 v71, v70
	s_nop 0
	v_fma_f32 v72, -v70, v71, 1.0
	v_fmac_f32_e32 v71, v72, v71
	v_div_scale_f32 v72, vcc, 1.0, v69, 1.0
	v_mul_f32_e32 v73, v72, v71
	v_fma_f32 v74, -v70, v73, v72
	v_fmac_f32_e32 v73, v74, v71
	v_fma_f32 v70, -v70, v73, v72
	v_div_fmas_f32 v70, v70, v71, v73
	v_div_fixup_f32 v69, v70, v69, 1.0
	v_div_scale_f32 v70, s[2:3], v68, v68, 1.0
	v_rcp_f32_e32 v71, v70
	s_nop 0
	v_fma_f32 v72, -v70, v71, 1.0
	v_fmac_f32_e32 v71, v72, v71
	v_div_scale_f32 v72, vcc, 1.0, v68, 1.0
	v_mul_f32_e32 v73, v72, v71
	v_fma_f32 v74, -v70, v73, v72
	v_fmac_f32_e32 v73, v74, v71
	v_fma_f32 v70, -v70, v73, v72
	v_div_fmas_f32 v70, v70, v71, v73
	v_div_fixup_f32 v68, v70, v68, 1.0
	v_pk_fma_f32 v[160:161], v[50:51], v[68:69], v[160:161]
	s_waitcnt vmcnt(30)
	v_cvt_f32_f16_e32 v68, v194
	v_cvt_f32_f16_e32 v69, v195
	v_add_u32_e32 v96, 0x7b400, v94
	global_load_ushort v194, v96, s[40:41]
	v_add_u32_e32 v96, 0x7ee00, v94
	global_load_ushort v195, v96, s[40:41]
	v_mul_f32_e32 v68, 0xbfb8aa3b, v68
	v_mul_f32_e32 v69, 0xbfb8aa3b, v69
	v_exp_f32_e32 v68, v68
	v_exp_f32_e32 v69, v69
	s_nop 0
	v_pk_add_f32 v[68:69], v[68:69], 1.0 op_sel_hi:[1,0]
	s_nop 0
	v_div_scale_f32 v70, s[2:3], v69, v69, 1.0
	v_rcp_f32_e32 v71, v70
	s_nop 0
	v_fma_f32 v72, -v70, v71, 1.0
	v_fmac_f32_e32 v71, v72, v71
	v_div_scale_f32 v72, vcc, 1.0, v69, 1.0
	v_mul_f32_e32 v73, v72, v71
	v_fma_f32 v74, -v70, v73, v72
	v_fmac_f32_e32 v73, v74, v71
	v_fma_f32 v70, -v70, v73, v72
	v_div_fmas_f32 v70, v70, v71, v73
	v_div_fixup_f32 v69, v70, v69, 1.0
	v_div_scale_f32 v70, s[2:3], v68, v68, 1.0
	v_rcp_f32_e32 v71, v70
	s_nop 0
	v_fma_f32 v72, -v70, v71, 1.0
	v_fmac_f32_e32 v71, v72, v71
	v_div_scale_f32 v72, vcc, 1.0, v68, 1.0
	v_mul_f32_e32 v73, v72, v71
	v_fma_f32 v74, -v70, v73, v72
	v_fmac_f32_e32 v73, v74, v71
	v_fma_f32 v70, -v70, v73, v72
	v_div_fmas_f32 v70, v70, v71, v73
	v_div_fixup_f32 v68, v70, v68, 1.0
	v_pk_fma_f32 v[158:159], v[52:53], v[68:69], v[158:159]
	s_waitcnt vmcnt(30)
; __device__ __forceinline__ float sigmoidf_(float x) { return 1.f / (1.f + __expf(-x)); }
; __device__ __forceinline__ void phase_merge(const KP& p, char* smem, int* q, int xcc) {
;     ...
;           [&](int mi, int ni, int r, int row, int col, float v) {
;             const float gz = (float)G[(size_t)row * NU + col];
;             tot[mi][ni][r] += sigmoidf_(gz) * v;
;           },
	v_cvt_f32_f16_e32 v68, v196
	v_cvt_f32_f16_e32 v69, v197
	v_add_u32_e32 v96, 0x91000, v94
	global_load_ushort v196, v96, s[40:41]
	v_add_u32_e32 v96, 0x94a00, v94
	global_load_ushort v197, v96, s[40:41]
	v_mul_f32_e32 v68, 0xbfb8aa3b, v68
	v_mul_f32_e32 v69, 0xbfb8aa3b, v69
	v_exp_f32_e32 v68, v68
	v_exp_f32_e32 v69, v69
	s_nop 0
	v_pk_add_f32 v[68:69], v[68:69], 1.0 op_sel_hi:[1,0]
	s_nop 0
	v_div_scale_f32 v70, s[2:3], v69, v69, 1.0
	v_rcp_f32_e32 v71, v70
	s_nop 0
	v_fma_f32 v72, -v70, v71, 1.0
	v_fmac_f32_e32 v71, v72, v71
	v_div_scale_f32 v72, vcc, 1.0, v69, 1.0
	v_mul_f32_e32 v73, v72, v71
	v_fma_f32 v74, -v70, v73, v72
	v_fmac_f32_e32 v73, v74, v71
	v_fma_f32 v70, -v70, v73, v72
	v_div_fmas_f32 v70, v70, v71, v73
	v_div_fixup_f32 v69, v70, v69, 1.0
	v_div_scale_f32 v70, s[2:3], v68, v68, 1.0
	v_rcp_f32_e32 v71, v70
	s_nop 0
	v_fma_f32 v72, -v70, v71, 1.0
	v_fmac_f32_e32 v71, v72, v71
	v_div_scale_f32 v72, vcc, 1.0, v68, 1.0
	v_mul_f32_e32 v73, v72, v71
	v_fma_f32 v74, -v70, v73, v72
	v_fmac_f32_e32 v73, v74, v71
	v_fma_f32 v70, -v70, v73, v72
	v_div_fmas_f32 v70, v70, v71, v73
	v_div_fixup_f32 v68, v70, v68, 1.0
	v_pk_fma_f32 v[156:157], v[54:55], v[68:69], v[156:157]
	s_waitcnt vmcnt(30)
	v_cvt_f32_f16_e32 v68, v198
	v_cvt_f32_f16_e32 v69, v199
	v_add_u32_e32 v96, 0x98400, v94
	global_load_ushort v198, v96, s[40:41]
	v_add_u32_e32 v96, 0x9be00, v94
	global_load_ushort v199, v96, s[40:41]
	v_mul_f32_e32 v68, 0xbfb8aa3b, v68
	v_mul_f32_e32 v69, 0xbfb8aa3b, v69
	v_exp_f32_e32 v68, v68
	v_exp_f32_e32 v69, v69
	s_nop 0
	v_pk_add_f32 v[68:69], v[68:69], 1.0 op_sel_hi:[1,0]
	s_nop 0
	v_div_scale_f32 v70, s[2:3], v69, v69, 1.0
	v_rcp_f32_e32 v71, v70
	s_nop 0
	v_fma_f32 v72, -v70, v71, 1.0
	v_fmac_f32_e32 v71, v72, v71
	v_div_scale_f32 v72, vcc, 1.0, v69, 1.0
	v_mul_f32_e32 v73, v72, v71
	v_fma_f32 v74, -v70, v73, v72
	v_fmac_f32_e32 v73, v74, v71
	v_fma_f32 v70, -v70, v73, v72
	v_div_fmas_f32 v70, v70, v71, v73
	v_div_fixup_f32 v69, v70, v69, 1.0
	v_div_scale_f32 v70, s[2:3], v68, v68, 1.0
	v_rcp_f32_e32 v71, v70
	s_nop 0
	v_fma_f32 v72, -v70, v71, 1.0
	v_fmac_f32_e32 v71, v72, v71
	v_div_scale_f32 v72, vcc, 1.0, v68, 1.0
	v_mul_f32_e32 v73, v72, v71
	v_fma_f32 v74, -v70, v73, v72
	v_fmac_f32_e32 v73, v74, v71
	v_fma_f32 v70, -v70, v73, v72
	v_div_fmas_f32 v70, v70, v71, v73
	v_div_fixup_f32 v68, v70, v68, 1.0
	v_pk_fma_f32 v[154:155], v[56:57], v[68:69], v[154:155]
	s_waitcnt vmcnt(30)
	v_cvt_f32_f16_e32 v68, v200
	v_cvt_f32_f16_e32 v69, v201
	v_add_u32_e32 v96, 0xae000, v94
	global_load_ushort v200, v96, s[40:41]
	v_add_u32_e32 v96, 0xb1a00, v94
	global_load_ushort v201, v96, s[40:41]
	v_mul_f32_e32 v68, 0xbfb8aa3b, v68
	v_mul_f32_e32 v69, 0xbfb8aa3b, v69
	v_exp_f32_e32 v68, v68
	v_exp_f32_e32 v69, v69
	s_nop 0
	v_pk_add_f32 v[68:69], v[68:69], 1.0 op_sel_hi:[1,0]
	s_nop 0
	v_div_scale_f32 v70, s[2:3], v69, v69, 1.0
	v_rcp_f32_e32 v71, v70
	s_nop 0
	v_fma_f32 v72, -v70, v71, 1.0
	v_fmac_f32_e32 v71, v72, v71
	v_div_scale_f32 v72, vcc, 1.0, v69, 1.0
	v_mul_f32_e32 v73, v72, v71
	v_fma_f32 v74, -v70, v73, v72
	v_fmac_f32_e32 v73, v74, v71
	v_fma_f32 v70, -v70, v73, v72
	v_div_fmas_f32 v70, v70, v71, v73
	v_div_fixup_f32 v69, v70, v69, 1.0
	v_div_scale_f32 v70, s[2:3], v68, v68, 1.0
	v_rcp_f32_e32 v71, v70
	s_nop 0
	v_fma_f32 v72, -v70, v71, 1.0
	v_fmac_f32_e32 v71, v72, v71
	v_div_scale_f32 v72, vcc, 1.0, v68, 1.0
	v_mul_f32_e32 v73, v72, v71
	v_fma_f32 v74, -v70, v73, v72
	v_fmac_f32_e32 v73, v74, v71
	v_fma_f32 v70, -v70, v73, v72
	v_div_fmas_f32 v70, v70, v71, v73
	v_div_fixup_f32 v68, v70, v68, 1.0
	v_pk_fma_f32 v[152:153], v[58:59], v[68:69], v[152:153]
	s_waitcnt vmcnt(30)
	v_cvt_f32_f16_e32 v68, v202
	v_cvt_f32_f16_e32 v69, v203
	v_add_u32_e32 v96, 0xb5400, v94
	global_load_ushort v202, v96, s[40:41]
	v_add_u32_e32 v96, 0xb8e00, v94
	global_load_ushort v203, v96, s[40:41]
	v_mul_f32_e32 v68, 0xbfb8aa3b, v68
	v_mul_f32_e32 v69, 0xbfb8aa3b, v69
	v_exp_f32_e32 v68, v68
	v_exp_f32_e32 v69, v69
	s_nop 0
	v_pk_add_f32 v[68:69], v[68:69], 1.0 op_sel_hi:[1,0]
	s_nop 0
	v_div_scale_f32 v70, s[2:3], v69, v69, 1.0
	v_rcp_f32_e32 v71, v70
	s_nop 0
	v_fma_f32 v72, -v70, v71, 1.0
	v_fmac_f32_e32 v71, v72, v71
	v_div_scale_f32 v72, vcc, 1.0, v69, 1.0
	v_mul_f32_e32 v73, v72, v71
	v_fma_f32 v74, -v70, v73, v72
	v_fmac_f32_e32 v73, v74, v71
	v_fma_f32 v70, -v70, v73, v72
	v_div_fmas_f32 v70, v70, v71, v73
	v_div_fixup_f32 v69, v70, v69, 1.0
	v_div_scale_f32 v70, s[2:3], v68, v68, 1.0
	v_rcp_f32_e32 v71, v70
	s_nop 0
	v_fma_f32 v72, -v70, v71, 1.0
	v_fmac_f32_e32 v71, v72, v71
	v_div_scale_f32 v72, vcc, 1.0, v68, 1.0
	v_mul_f32_e32 v73, v72, v71
	v_fma_f32 v74, -v70, v73, v72
	v_fmac_f32_e32 v73, v74, v71
	v_fma_f32 v70, -v70, v73, v72
	v_div_fmas_f32 v70, v70, v71, v73
	v_div_fixup_f32 v68, v70, v68, 1.0
	v_pk_fma_f32 v[150:151], v[60:61], v[68:69], v[150:151]
	s_waitcnt vmcnt(30)
	v_cvt_f32_f16_e32 v68, v204
	v_cvt_f32_f16_e32 v69, v205
	v_add_u32_e32 v96, 0xcb000, v94
	global_load_ushort v204, v96, s[40:41]
	v_add_u32_e32 v96, 0xcea00, v94
	global_load_ushort v205, v96, s[40:41]
	v_mul_f32_e32 v68, 0xbfb8aa3b, v68
	v_mul_f32_e32 v69, 0xbfb8aa3b, v69
	v_exp_f32_e32 v68, v68
	v_exp_f32_e32 v69, v69
	s_nop 0
	v_pk_add_f32 v[68:69], v[68:69], 1.0 op_sel_hi:[1,0]
	s_nop 0
	v_div_scale_f32 v70, s[2:3], v69, v69, 1.0
	v_rcp_f32_e32 v71, v70
	s_nop 0
	v_fma_f32 v72, -v70, v71, 1.0
	v_fmac_f32_e32 v71, v72, v71
	v_div_scale_f32 v72, vcc, 1.0, v69, 1.0
	v_mul_f32_e32 v73, v72, v71
	v_fma_f32 v74, -v70, v73, v72
	v_fmac_f32_e32 v73, v74, v71
	v_fma_f32 v70, -v70, v73, v72
	v_div_fmas_f32 v70, v70, v71, v73
	v_div_fixup_f32 v69, v70, v69, 1.0
	v_div_scale_f32 v70, s[2:3], v68, v68, 1.0
	v_rcp_f32_e32 v71, v70
	s_nop 0
	v_fma_f32 v72, -v70, v71, 1.0
	v_fmac_f32_e32 v71, v72, v71
	v_div_scale_f32 v72, vcc, 1.0, v68, 1.0
	v_mul_f32_e32 v73, v72, v71
	v_fma_f32 v74, -v70, v73, v72
	v_fmac_f32_e32 v73, v74, v71
	v_fma_f32 v70, -v70, v73, v72
	v_div_fmas_f32 v70, v70, v71, v73
	v_div_fixup_f32 v68, v70, v68, 1.0
	v_pk_fma_f32 v[148:149], v[62:63], v[68:69], v[148:149]
	s_waitcnt vmcnt(30)
; __device__ __forceinline__ float sigmoidf_(float x) { return 1.f / (1.f + __expf(-x)); }
; __device__ __forceinline__ void phase_merge(const KP& p, char* smem, int* q, int xcc) {
;     ...
;           [&](int mi, int ni, int r, int row, int col, float v) {
;             const float gz = (float)G[(size_t)row * NU + col];
;             tot[mi][ni][r] += sigmoidf_(gz) * v;
;           },
	v_cvt_f32_f16_e32 v68, v206
	v_cvt_f32_f16_e32 v69, v207
	v_add_u32_e32 v96, 0xd2400, v94
	global_load_ushort v206, v96, s[40:41]
	v_add_u32_e32 v96, 0xd5e00, v94
	global_load_ushort v207, v96, s[40:41]
	v_mul_f32_e32 v68, 0xbfb8aa3b, v68
	v_mul_f32_e32 v69, 0xbfb8aa3b, v69
	v_exp_f32_e32 v68, v68
	v_exp_f32_e32 v69, v69
	s_nop 0
	v_pk_add_f32 v[68:69], v[68:69], 1.0 op_sel_hi:[1,0]
	s_nop 0
	v_div_scale_f32 v70, s[2:3], v69, v69, 1.0
	v_rcp_f32_e32 v71, v70
	s_nop 0
	v_fma_f32 v72, -v70, v71, 1.0
	v_fmac_f32_e32 v71, v72, v71
	v_div_scale_f32 v72, vcc, 1.0, v69, 1.0
	v_mul_f32_e32 v73, v72, v71
	v_fma_f32 v74, -v70, v73, v72
	v_fmac_f32_e32 v73, v74, v71
	v_fma_f32 v70, -v70, v73, v72
	v_div_fmas_f32 v70, v70, v71, v73
	v_div_fixup_f32 v69, v70, v69, 1.0
	v_div_scale_f32 v70, s[2:3], v68, v68, 1.0
	v_rcp_f32_e32 v71, v70
	s_nop 0
	v_fma_f32 v72, -v70, v71, 1.0
	v_fmac_f32_e32 v71, v72, v71
	v_div_scale_f32 v72, vcc, 1.0, v68, 1.0
	v_mul_f32_e32 v73, v72, v71
	v_fma_f32 v74, -v70, v73, v72
	v_fmac_f32_e32 v73, v74, v71
	v_fma_f32 v70, -v70, v73, v72
	v_div_fmas_f32 v70, v70, v71, v73
	v_div_fixup_f32 v68, v70, v68, 1.0
	v_pk_fma_f32 v[146:147], v[64:65], v[68:69], v[146:147]
	s_waitcnt vmcnt(30)
	v_cvt_f32_f16_e32 v68, v208
	v_cvt_f32_f16_e32 v69, v209
	v_add_u32_e32 v96, 0x74000, v94
	global_load_ushort v208, v96, s[40:41] offset:64
	v_add_u32_e32 v96, 0x77a00, v94
	global_load_ushort v209, v96, s[40:41] offset:64
	v_mul_f32_e32 v68, 0xbfb8aa3b, v68
	v_mul_f32_e32 v69, 0xbfb8aa3b, v69
	v_exp_f32_e32 v68, v68
	v_exp_f32_e32 v69, v69
	s_nop 0
	v_pk_add_f32 v[68:69], v[68:69], 1.0 op_sel_hi:[1,0]
	s_nop 0
	v_div_scale_f32 v70, s[2:3], v69, v69, 1.0
	v_rcp_f32_e32 v71, v70
	s_nop 0
	v_fma_f32 v72, -v70, v71, 1.0
	v_fmac_f32_e32 v71, v72, v71
	v_div_scale_f32 v72, vcc, 1.0, v69, 1.0
	v_mul_f32_e32 v73, v72, v71
	v_fma_f32 v74, -v70, v73, v72
	v_fmac_f32_e32 v73, v74, v71
	v_fma_f32 v70, -v70, v73, v72
	v_div_fmas_f32 v70, v70, v71, v73
	v_div_fixup_f32 v69, v70, v69, 1.0
	v_div_scale_f32 v70, s[2:3], v68, v68, 1.0
	v_rcp_f32_e32 v71, v70
	s_nop 0
	v_fma_f32 v72, -v70, v71, 1.0
	v_fmac_f32_e32 v71, v72, v71
	v_div_scale_f32 v72, vcc, 1.0, v68, 1.0
	v_mul_f32_e32 v73, v72, v71
	v_fma_f32 v74, -v70, v73, v72
	v_fmac_f32_e32 v73, v74, v71
	v_fma_f32 v70, -v70, v73, v72
	v_div_fmas_f32 v70, v70, v71, v73
	v_div_fixup_f32 v68, v70, v68, 1.0
	v_pk_fma_f32 v[144:145], v[34:35], v[68:69], v[144:145]
	s_waitcnt vmcnt(30)
	v_cvt_f32_f16_e32 v68, v210
	v_cvt_f32_f16_e32 v69, v211
	v_add_u32_e32 v96, 0x7b400, v94
	global_load_ushort v210, v96, s[40:41] offset:64
	v_add_u32_e32 v96, 0x7ee00, v94
	global_load_ushort v211, v96, s[40:41] offset:64
	v_mul_f32_e32 v68, 0xbfb8aa3b, v68
	v_mul_f32_e32 v69, 0xbfb8aa3b, v69
	v_exp_f32_e32 v68, v68
	v_exp_f32_e32 v69, v69
	s_nop 0
	v_pk_add_f32 v[68:69], v[68:69], 1.0 op_sel_hi:[1,0]
	s_nop 0
	v_div_scale_f32 v70, s[2:3], v69, v69, 1.0
	v_rcp_f32_e32 v71, v70
	s_nop 0
	v_fma_f32 v72, -v70, v71, 1.0
	v_fmac_f32_e32 v71, v72, v71
	v_div_scale_f32 v72, vcc, 1.0, v69, 1.0
	v_mul_f32_e32 v73, v72, v71
	v_fma_f32 v74, -v70, v73, v72
	v_fmac_f32_e32 v73, v74, v71
	v_fma_f32 v70, -v70, v73, v72
	v_div_fmas_f32 v70, v70, v71, v73
	v_div_fixup_f32 v69, v70, v69, 1.0
	v_div_scale_f32 v70, s[2:3], v68, v68, 1.0
	v_rcp_f32_e32 v71, v70
	s_nop 0
	v_fma_f32 v72, -v70, v71, 1.0
	v_fmac_f32_e32 v71, v72, v71
	v_div_scale_f32 v72, vcc, 1.0, v68, 1.0
	v_mul_f32_e32 v73, v72, v71
	v_fma_f32 v74, -v70, v73, v72
	v_fmac_f32_e32 v73, v74, v71
	v_fma_f32 v70, -v70, v73, v72
	v_div_fmas_f32 v70, v70, v71, v73
	v_div_fixup_f32 v68, v70, v68, 1.0
	v_pk_fma_f32 v[142:143], v[36:37], v[68:69], v[142:143]
	s_waitcnt vmcnt(30)
	v_cvt_f32_f16_e32 v68, v212
	v_cvt_f32_f16_e32 v69, v213
	v_add_u32_e32 v96, 0x91000, v94
	global_load_ushort v212, v96, s[40:41] offset:64
	v_add_u32_e32 v96, 0x94a00, v94
	global_load_ushort v213, v96, s[40:41] offset:64
	v_mul_f32_e32 v68, 0xbfb8aa3b, v68
	v_mul_f32_e32 v69, 0xbfb8aa3b, v69
	v_exp_f32_e32 v68, v68
	v_exp_f32_e32 v69, v69
	s_nop 0
	v_pk_add_f32 v[68:69], v[68:69], 1.0 op_sel_hi:[1,0]
	s_nop 0
	v_div_scale_f32 v70, s[2:3], v69, v69, 1.0
	v_rcp_f32_e32 v71, v70
	s_nop 0
	v_fma_f32 v72, -v70, v71, 1.0
	v_fmac_f32_e32 v71, v72, v71
	v_div_scale_f32 v72, vcc, 1.0, v69, 1.0
	v_mul_f32_e32 v73, v72, v71
	v_fma_f32 v74, -v70, v73, v72
	v_fmac_f32_e32 v73, v74, v71
	v_fma_f32 v70, -v70, v73, v72
	v_div_fmas_f32 v70, v70, v71, v73
	v_div_fixup_f32 v69, v70, v69, 1.0
	v_div_scale_f32 v70, s[2:3], v68, v68, 1.0
	v_rcp_f32_e32 v71, v70
	s_nop 0
	v_fma_f32 v72, -v70, v71, 1.0
	v_fmac_f32_e32 v71, v72, v71
	v_div_scale_f32 v72, vcc, 1.0, v68, 1.0
	v_mul_f32_e32 v73, v72, v71
	v_fma_f32 v74, -v70, v73, v72
	v_fmac_f32_e32 v73, v74, v71
	v_fma_f32 v70, -v70, v73, v72
	v_div_fmas_f32 v70, v70, v71, v73
	v_div_fixup_f32 v68, v70, v68, 1.0
	v_pk_fma_f32 v[140:141], v[38:39], v[68:69], v[140:141]
	s_waitcnt vmcnt(30)
	v_cvt_f32_f16_e32 v68, v214
	v_cvt_f32_f16_e32 v69, v215
	v_add_u32_e32 v96, 0x98400, v94
	global_load_ushort v214, v96, s[40:41] offset:64
	v_add_u32_e32 v96, 0x9be00, v94
	global_load_ushort v215, v96, s[40:41] offset:64
	v_mul_f32_e32 v68, 0xbfb8aa3b, v68
	v_mul_f32_e32 v69, 0xbfb8aa3b, v69
	v_exp_f32_e32 v68, v68
	v_exp_f32_e32 v69, v69
	s_nop 0
	v_pk_add_f32 v[68:69], v[68:69], 1.0 op_sel_hi:[1,0]
	s_nop 0
	v_div_scale_f32 v70, s[2:3], v69, v69, 1.0
	v_rcp_f32_e32 v71, v70
	s_nop 0
	v_fma_f32 v72, -v70, v71, 1.0
	v_fmac_f32_e32 v71, v72, v71
	v_div_scale_f32 v72, vcc, 1.0, v69, 1.0
	v_mul_f32_e32 v73, v72, v71
	v_fma_f32 v74, -v70, v73, v72
	v_fmac_f32_e32 v73, v74, v71
	v_fma_f32 v70, -v70, v73, v72
	v_div_fmas_f32 v70, v70, v71, v73
	v_div_fixup_f32 v69, v70, v69, 1.0
	v_div_scale_f32 v70, s[2:3], v68, v68, 1.0
	v_rcp_f32_e32 v71, v70
	s_nop 0
	v_fma_f32 v72, -v70, v71, 1.0
	v_fmac_f32_e32 v71, v72, v71
	v_div_scale_f32 v72, vcc, 1.0, v68, 1.0
	v_mul_f32_e32 v73, v72, v71
	v_fma_f32 v74, -v70, v73, v72
	v_fmac_f32_e32 v73, v74, v71
	v_fma_f32 v70, -v70, v73, v72
	v_div_fmas_f32 v70, v70, v71, v73
	v_div_fixup_f32 v68, v70, v68, 1.0
	v_pk_fma_f32 v[138:139], v[40:41], v[68:69], v[138:139]
	s_waitcnt vmcnt(30)
; __device__ __forceinline__ float sigmoidf_(float x) { return 1.f / (1.f + __expf(-x)); }
; __device__ __forceinline__ void phase_merge(const KP& p, char* smem, int* q, int xcc) {
;     ...
;           [&](int mi, int ni, int r, int row, int col, float v) {
;             const float gz = (float)G[(size_t)row * NU + col];
;             tot[mi][ni][r] += sigmoidf_(gz) * v;
;           },
	v_cvt_f32_f16_e32 v68, v216
	v_cvt_f32_f16_e32 v69, v217
	v_add_u32_e32 v96, 0xae000, v94
	global_load_ushort v216, v96, s[40:41] offset:64
	v_add_u32_e32 v96, 0xb1a00, v94
	global_load_ushort v217, v96, s[40:41] offset:64
	v_mul_f32_e32 v68, 0xbfb8aa3b, v68
	v_mul_f32_e32 v69, 0xbfb8aa3b, v69
	v_exp_f32_e32 v68, v68
	v_exp_f32_e32 v69, v69
	s_nop 0
	v_pk_add_f32 v[68:69], v[68:69], 1.0 op_sel_hi:[1,0]
	s_nop 0
	v_div_scale_f32 v70, s[2:3], v69, v69, 1.0
	v_rcp_f32_e32 v71, v70
	s_nop 0
	v_fma_f32 v72, -v70, v71, 1.0
	v_fmac_f32_e32 v71, v72, v71
	v_div_scale_f32 v72, vcc, 1.0, v69, 1.0
	v_mul_f32_e32 v73, v72, v71
	v_fma_f32 v74, -v70, v73, v72
	v_fmac_f32_e32 v73, v74, v71
	v_fma_f32 v70, -v70, v73, v72
	v_div_fmas_f32 v70, v70, v71, v73
	v_div_fixup_f32 v69, v70, v69, 1.0
	v_div_scale_f32 v70, s[2:3], v68, v68, 1.0
	v_rcp_f32_e32 v71, v70
	s_nop 0
	v_fma_f32 v72, -v70, v71, 1.0
	v_fmac_f32_e32 v71, v72, v71
	v_div_scale_f32 v72, vcc, 1.0, v68, 1.0
	v_mul_f32_e32 v73, v72, v71
	v_fma_f32 v74, -v70, v73, v72
	v_fmac_f32_e32 v73, v74, v71
	v_fma_f32 v70, -v70, v73, v72
	v_div_fmas_f32 v70, v70, v71, v73
	v_div_fixup_f32 v68, v70, v68, 1.0
	v_pk_fma_f32 v[136:137], v[42:43], v[68:69], v[136:137]
	s_waitcnt vmcnt(30)
	v_cvt_f32_f16_e32 v68, v218
	v_cvt_f32_f16_e32 v69, v219
	v_add_u32_e32 v96, 0xb5400, v94
	global_load_ushort v218, v96, s[40:41] offset:64
	v_add_u32_e32 v96, 0xb8e00, v94
	global_load_ushort v219, v96, s[40:41] offset:64
	v_mul_f32_e32 v68, 0xbfb8aa3b, v68
	v_mul_f32_e32 v69, 0xbfb8aa3b, v69
	v_exp_f32_e32 v68, v68
	v_exp_f32_e32 v69, v69
	s_nop 0
	v_pk_add_f32 v[68:69], v[68:69], 1.0 op_sel_hi:[1,0]
	s_nop 0
	v_div_scale_f32 v70, s[2:3], v69, v69, 1.0
	v_rcp_f32_e32 v71, v70
	s_nop 0
	v_fma_f32 v72, -v70, v71, 1.0
	v_fmac_f32_e32 v71, v72, v71
	v_div_scale_f32 v72, vcc, 1.0, v69, 1.0
	v_mul_f32_e32 v73, v72, v71
	v_fma_f32 v74, -v70, v73, v72
	v_fmac_f32_e32 v73, v74, v71
	v_fma_f32 v70, -v70, v73, v72
	v_div_fmas_f32 v70, v70, v71, v73
	v_div_fixup_f32 v69, v70, v69, 1.0
	v_div_scale_f32 v70, s[2:3], v68, v68, 1.0
	v_rcp_f32_e32 v71, v70
	s_nop 0
	v_fma_f32 v72, -v70, v71, 1.0
	v_fmac_f32_e32 v71, v72, v71
	v_div_scale_f32 v72, vcc, 1.0, v68, 1.0
	v_mul_f32_e32 v73, v72, v71
	v_fma_f32 v74, -v70, v73, v72
	v_fmac_f32_e32 v73, v74, v71
	v_fma_f32 v70, -v70, v73, v72
	v_div_fmas_f32 v70, v70, v71, v73
	v_div_fixup_f32 v68, v70, v68, 1.0
	v_pk_fma_f32 v[134:135], v[44:45], v[68:69], v[134:135]
	s_waitcnt vmcnt(30)
	v_cvt_f32_f16_e32 v68, v220
	v_cvt_f32_f16_e32 v69, v221
	v_add_u32_e32 v96, 0xcb000, v94
	global_load_ushort v220, v96, s[40:41] offset:64
	v_add_u32_e32 v96, 0xcea00, v94
	global_load_ushort v221, v96, s[40:41] offset:64
	v_mul_f32_e32 v68, 0xbfb8aa3b, v68
	v_mul_f32_e32 v69, 0xbfb8aa3b, v69
	v_exp_f32_e32 v68, v68
	v_exp_f32_e32 v69, v69
	s_nop 0
	v_pk_add_f32 v[68:69], v[68:69], 1.0 op_sel_hi:[1,0]
	s_nop 0
	v_div_scale_f32 v70, s[2:3], v69, v69, 1.0
	v_rcp_f32_e32 v71, v70
	s_nop 0
	v_fma_f32 v72, -v70, v71, 1.0
	v_fmac_f32_e32 v71, v72, v71
	v_div_scale_f32 v72, vcc, 1.0, v69, 1.0
	v_mul_f32_e32 v73, v72, v71
	v_fma_f32 v74, -v70, v73, v72
	v_fmac_f32_e32 v73, v74, v71
	v_fma_f32 v70, -v70, v73, v72
	v_div_fmas_f32 v70, v70, v71, v73
	v_div_fixup_f32 v69, v70, v69, 1.0
	v_div_scale_f32 v70, s[2:3], v68, v68, 1.0
	v_rcp_f32_e32 v71, v70
	s_nop 0
	v_fma_f32 v72, -v70, v71, 1.0
	v_fmac_f32_e32 v71, v72, v71
	v_div_scale_f32 v72, vcc, 1.0, v68, 1.0
	v_mul_f32_e32 v73, v72, v71
	v_fma_f32 v74, -v70, v73, v72
	v_fmac_f32_e32 v73, v74, v71
	v_fma_f32 v70, -v70, v73, v72
	v_div_fmas_f32 v70, v70, v71, v73
	v_div_fixup_f32 v68, v70, v68, 1.0
	v_pk_fma_f32 v[132:133], v[46:47], v[68:69], v[132:133]
	s_waitcnt vmcnt(30)
	v_cvt_f32_f16_e32 v68, v222
	v_cvt_f32_f16_e32 v69, v223
	v_add_u32_e32 v96, 0xd2400, v94
	global_load_ushort v222, v96, s[40:41] offset:64
	v_add_u32_e32 v96, 0xd5e00, v94
	global_load_ushort v223, v96, s[40:41] offset:64
	v_mul_f32_e32 v68, 0xbfb8aa3b, v68
	v_mul_f32_e32 v69, 0xbfb8aa3b, v69
	v_exp_f32_e32 v68, v68
	v_exp_f32_e32 v69, v69
	s_nop 0
	v_pk_add_f32 v[68:69], v[68:69], 1.0 op_sel_hi:[1,0]
	s_nop 0
	v_div_scale_f32 v70, s[2:3], v69, v69, 1.0
	v_rcp_f32_e32 v71, v70
	s_nop 0
	v_fma_f32 v72, -v70, v71, 1.0
	v_fmac_f32_e32 v71, v72, v71
	v_div_scale_f32 v72, vcc, 1.0, v69, 1.0
	v_mul_f32_e32 v73, v72, v71
	v_fma_f32 v74, -v70, v73, v72
	v_fmac_f32_e32 v73, v74, v71
	v_fma_f32 v70, -v70, v73, v72
	v_div_fmas_f32 v70, v70, v71, v73
	v_div_fixup_f32 v69, v70, v69, 1.0
	v_div_scale_f32 v70, s[2:3], v68, v68, 1.0
	v_rcp_f32_e32 v71, v70
	s_nop 0
	v_fma_f32 v72, -v70, v71, 1.0
	v_fmac_f32_e32 v71, v72, v71
	v_div_scale_f32 v72, vcc, 1.0, v68, 1.0
	v_mul_f32_e32 v73, v72, v71
	v_fma_f32 v74, -v70, v73, v72
	v_fmac_f32_e32 v73, v74, v71
	v_fma_f32 v70, -v70, v73, v72
	v_div_fmas_f32 v70, v70, v71, v73
	v_div_fixup_f32 v68, v70, v68, 1.0
	v_pk_fma_f32 v[130:131], v[48:49], v[68:69], v[130:131]
	s_waitcnt vmcnt(30)
	v_cvt_f32_f16_e32 v68, v192
	v_cvt_f32_f16_e32 v69, v193
	v_mul_f32_e32 v68, 0xbfb8aa3b, v68
	v_mul_f32_e32 v69, 0xbfb8aa3b, v69
	v_exp_f32_e32 v68, v68
	v_exp_f32_e32 v69, v69
	s_nop 0
	v_pk_add_f32 v[68:69], v[68:69], 1.0 op_sel_hi:[1,0]
	s_nop 0
	v_div_scale_f32 v70, s[2:3], v69, v69, 1.0
	v_rcp_f32_e32 v71, v70
	s_nop 0
	v_fma_f32 v72, -v70, v71, 1.0
	v_fmac_f32_e32 v71, v72, v71
	v_div_scale_f32 v72, vcc, 1.0, v69, 1.0
	v_mul_f32_e32 v73, v72, v71
	v_fma_f32 v74, -v70, v73, v72
	v_fmac_f32_e32 v73, v74, v71
	v_fma_f32 v70, -v70, v73, v72
	v_div_fmas_f32 v70, v70, v71, v73
	v_div_fixup_f32 v69, v70, v69, 1.0
	v_div_scale_f32 v70, s[2:3], v68, v68, 1.0
	v_rcp_f32_e32 v71, v70
	s_nop 0
	v_fma_f32 v72, -v70, v71, 1.0
	v_fmac_f32_e32 v71, v72, v71
	v_div_scale_f32 v72, vcc, 1.0, v68, 1.0
	v_mul_f32_e32 v73, v72, v71
	v_fma_f32 v74, -v70, v73, v72
	v_fmac_f32_e32 v73, v74, v71
	v_fma_f32 v70, -v70, v73, v72
	v_div_fmas_f32 v70, v70, v71, v73
	v_div_fixup_f32 v68, v70, v68, 1.0
	v_pk_fma_f32 v[128:129], v[18:19], v[68:69], v[128:129]
	s_waitcnt vmcnt(28)
;   __device__ __forceinline__ const float* x() const { return (const float*)(const __attribute__((address_space(1))) float*)kp[0]; }
; __device__ __forceinline__ float sigmoidf_(float x) { return 1.f / (1.f + __expf(-x)); }
; __device__ __forceinline__ void phase_merge(const KP& p, char* smem, int* q, int xcc) {
;     ...
;           [&](int mi, int ni, int r, int row, int col, float v) {
;             const float gz = (float)G[(size_t)row * NU + col];
;             tot[mi][ni][r] += sigmoidf_(gz) * v;
;           },
	v_cvt_f32_f16_e32 v68, v194
	v_cvt_f32_f16_e32 v69, v195
	v_mul_f32_e32 v68, 0xbfb8aa3b, v68
	v_mul_f32_e32 v69, 0xbfb8aa3b, v69
	v_exp_f32_e32 v68, v68
	v_exp_f32_e32 v69, v69
	s_nop 0
	v_pk_add_f32 v[68:69], v[68:69], 1.0 op_sel_hi:[1,0]
	s_nop 0
	v_div_scale_f32 v70, s[2:3], v69, v69, 1.0
	v_rcp_f32_e32 v71, v70
	s_nop 0
	v_fma_f32 v72, -v70, v71, 1.0
	v_fmac_f32_e32 v71, v72, v71
	v_div_scale_f32 v72, vcc, 1.0, v69, 1.0
	v_mul_f32_e32 v73, v72, v71
	v_fma_f32 v74, -v70, v73, v72
	v_fmac_f32_e32 v73, v74, v71
	v_fma_f32 v70, -v70, v73, v72
	v_div_fmas_f32 v70, v70, v71, v73
	v_div_fixup_f32 v69, v70, v69, 1.0
	v_div_scale_f32 v70, s[2:3], v68, v68, 1.0
	v_rcp_f32_e32 v71, v70
	s_nop 0
	v_fma_f32 v72, -v70, v71, 1.0
	v_fmac_f32_e32 v71, v72, v71
	v_div_scale_f32 v72, vcc, 1.0, v68, 1.0
	v_mul_f32_e32 v73, v72, v71
	v_fma_f32 v74, -v70, v73, v72
	v_fmac_f32_e32 v73, v74, v71
	v_fma_f32 v70, -v70, v73, v72
	v_div_fmas_f32 v70, v70, v71, v73
	v_div_fixup_f32 v68, v70, v68, 1.0
	v_pk_fma_f32 v[126:127], v[20:21], v[68:69], v[126:127]
	s_waitcnt vmcnt(26)
	v_cvt_f32_f16_e32 v68, v196
	v_cvt_f32_f16_e32 v69, v197
	v_mul_f32_e32 v68, 0xbfb8aa3b, v68
	v_mul_f32_e32 v69, 0xbfb8aa3b, v69
	v_exp_f32_e32 v68, v68
	v_exp_f32_e32 v69, v69
	s_nop 0
	v_pk_add_f32 v[68:69], v[68:69], 1.0 op_sel_hi:[1,0]
	s_nop 0
	v_div_scale_f32 v70, s[2:3], v69, v69, 1.0
	v_rcp_f32_e32 v71, v70
	s_nop 0
	v_fma_f32 v72, -v70, v71, 1.0
	v_fmac_f32_e32 v71, v72, v71
	v_div_scale_f32 v72, vcc, 1.0, v69, 1.0
	v_mul_f32_e32 v73, v72, v71
	v_fma_f32 v74, -v70, v73, v72
	v_fmac_f32_e32 v73, v74, v71
	v_fma_f32 v70, -v70, v73, v72
	v_div_fmas_f32 v70, v70, v71, v73
	v_div_fixup_f32 v69, v70, v69, 1.0
	v_div_scale_f32 v70, s[2:3], v68, v68, 1.0
	v_rcp_f32_e32 v71, v70
	s_nop 0
	v_fma_f32 v72, -v70, v71, 1.0
	v_fmac_f32_e32 v71, v72, v71
	v_div_scale_f32 v72, vcc, 1.0, v68, 1.0
	v_mul_f32_e32 v73, v72, v71
	v_fma_f32 v74, -v70, v73, v72
	v_fmac_f32_e32 v73, v74, v71
	v_fma_f32 v70, -v70, v73, v72
	v_div_fmas_f32 v70, v70, v71, v73
	v_div_fixup_f32 v68, v70, v68, 1.0
	v_pk_fma_f32 v[124:125], v[22:23], v[68:69], v[124:125]
	s_waitcnt vmcnt(24)
	v_cvt_f32_f16_e32 v68, v198
	v_cvt_f32_f16_e32 v69, v199
	v_mul_f32_e32 v68, 0xbfb8aa3b, v68
	v_mul_f32_e32 v69, 0xbfb8aa3b, v69
	v_exp_f32_e32 v68, v68
	v_exp_f32_e32 v69, v69
	s_nop 0
	v_pk_add_f32 v[68:69], v[68:69], 1.0 op_sel_hi:[1,0]
	s_nop 0
	v_div_scale_f32 v70, s[2:3], v69, v69, 1.0
	v_rcp_f32_e32 v71, v70
	s_nop 0
	v_fma_f32 v72, -v70, v71, 1.0
	v_fmac_f32_e32 v71, v72, v71
	v_div_scale_f32 v72, vcc, 1.0, v69, 1.0
	v_mul_f32_e32 v73, v72, v71
	v_fma_f32 v74, -v70, v73, v72
	v_fmac_f32_e32 v73, v74, v71
	v_fma_f32 v70, -v70, v73, v72
	v_div_fmas_f32 v70, v70, v71, v73
	v_div_fixup_f32 v69, v70, v69, 1.0
	v_div_scale_f32 v70, s[2:3], v68, v68, 1.0
	v_rcp_f32_e32 v71, v70
	s_nop 0
	v_fma_f32 v72, -v70, v71, 1.0
	v_fmac_f32_e32 v71, v72, v71
	v_div_scale_f32 v72, vcc, 1.0, v68, 1.0
	v_mul_f32_e32 v73, v72, v71
	v_fma_f32 v74, -v70, v73, v72
	v_fmac_f32_e32 v73, v74, v71
	v_fma_f32 v70, -v70, v73, v72
	v_div_fmas_f32 v70, v70, v71, v73
	v_div_fixup_f32 v68, v70, v68, 1.0
	v_pk_fma_f32 v[122:123], v[24:25], v[68:69], v[122:123]
	s_waitcnt vmcnt(22)
	v_cvt_f32_f16_e32 v68, v200
	v_cvt_f32_f16_e32 v69, v201
	v_mul_f32_e32 v68, 0xbfb8aa3b, v68
	v_mul_f32_e32 v69, 0xbfb8aa3b, v69
	v_exp_f32_e32 v68, v68
	v_exp_f32_e32 v69, v69
	s_nop 0
	v_pk_add_f32 v[68:69], v[68:69], 1.0 op_sel_hi:[1,0]
	s_nop 0
	v_div_scale_f32 v70, s[2:3], v69, v69, 1.0
	v_rcp_f32_e32 v71, v70
	s_nop 0
	v_fma_f32 v72, -v70, v71, 1.0
	v_fmac_f32_e32 v71, v72, v71
	v_div_scale_f32 v72, vcc, 1.0, v69, 1.0
	v_mul_f32_e32 v73, v72, v71
	v_fma_f32 v74, -v70, v73, v72
	v_fmac_f32_e32 v73, v74, v71
	v_fma_f32 v70, -v70, v73, v72
	v_div_fmas_f32 v70, v70, v71, v73
	v_div_fixup_f32 v69, v70, v69, 1.0
	v_div_scale_f32 v70, s[2:3], v68, v68, 1.0
	v_rcp_f32_e32 v71, v70
	s_nop 0
	v_fma_f32 v72, -v70, v71, 1.0
	v_fmac_f32_e32 v71, v72, v71
	v_div_scale_f32 v72, vcc, 1.0, v68, 1.0
	v_mul_f32_e32 v73, v72, v71
	v_fma_f32 v74, -v70, v73, v72
	v_fmac_f32_e32 v73, v74, v71
	v_fma_f32 v70, -v70, v73, v72
	v_div_fmas_f32 v70, v70, v71, v73
	v_div_fixup_f32 v68, v70, v68, 1.0
	v_pk_fma_f32 v[120:121], v[26:27], v[68:69], v[120:121]
	s_waitcnt vmcnt(20)
	v_cvt_f32_f16_e32 v68, v202
	v_cvt_f32_f16_e32 v69, v203
	v_mul_f32_e32 v68, 0xbfb8aa3b, v68
	v_mul_f32_e32 v69, 0xbfb8aa3b, v69
	v_exp_f32_e32 v68, v68
	v_exp_f32_e32 v69, v69
	s_nop 0
	v_pk_add_f32 v[68:69], v[68:69], 1.0 op_sel_hi:[1,0]
	s_nop 0
	v_div_scale_f32 v70, s[2:3], v69, v69, 1.0
	v_rcp_f32_e32 v71, v70
	s_nop 0
	v_fma_f32 v72, -v70, v71, 1.0
	v_fmac_f32_e32 v71, v72, v71
	v_div_scale_f32 v72, vcc, 1.0, v69, 1.0
	v_mul_f32_e32 v73, v72, v71
	v_fma_f32 v74, -v70, v73, v72
	v_fmac_f32_e32 v73, v74, v71
	v_fma_f32 v70, -v70, v73, v72
	v_div_fmas_f32 v70, v70, v71, v73
	v_div_fixup_f32 v69, v70, v69, 1.0
	v_div_scale_f32 v70, s[2:3], v68, v68, 1.0
	v_rcp_f32_e32 v71, v70
	s_nop 0
	v_fma_f32 v72, -v70, v71, 1.0
	v_fmac_f32_e32 v71, v72, v71
	v_div_scale_f32 v72, vcc, 1.0, v68, 1.0
	v_mul_f32_e32 v73, v72, v71
	v_fma_f32 v74, -v70, v73, v72
	v_fmac_f32_e32 v73, v74, v71
	v_fma_f32 v70, -v70, v73, v72
	v_div_fmas_f32 v70, v70, v71, v73
	v_div_fixup_f32 v68, v70, v68, 1.0
	v_pk_fma_f32 v[118:119], v[28:29], v[68:69], v[118:119]
	s_waitcnt vmcnt(18)
;   __device__ __forceinline__ const float* x() const { return (const float*)(const __attribute__((address_space(1))) float*)kp[0]; }
; __device__ __forceinline__ float sigmoidf_(float x) { return 1.f / (1.f + __expf(-x)); }
; __device__ __forceinline__ void phase_merge(const KP& p, char* smem, int* q, int xcc) {
;     ...
;           [&](int mi, int ni, int r, int row, int col, float v) {
;             const float gz = (float)G[(size_t)row * NU + col];
;             tot[mi][ni][r] += sigmoidf_(gz) * v;
;           },
	v_cvt_f32_f16_e32 v68, v204
	v_cvt_f32_f16_e32 v69, v205
	v_mul_f32_e32 v68, 0xbfb8aa3b, v68
	v_mul_f32_e32 v69, 0xbfb8aa3b, v69
	v_exp_f32_e32 v68, v68
	v_exp_f32_e32 v69, v69
	s_nop 0
	v_pk_add_f32 v[68:69], v[68:69], 1.0 op_sel_hi:[1,0]
	s_nop 0
	v_div_scale_f32 v70, s[2:3], v69, v69, 1.0
	v_rcp_f32_e32 v71, v70
	s_nop 0
	v_fma_f32 v72, -v70, v71, 1.0
	v_fmac_f32_e32 v71, v72, v71
	v_div_scale_f32 v72, vcc, 1.0, v69, 1.0
	v_mul_f32_e32 v73, v72, v71
	v_fma_f32 v74, -v70, v73, v72
	v_fmac_f32_e32 v73, v74, v71
	v_fma_f32 v70, -v70, v73, v72
	v_div_fmas_f32 v70, v70, v71, v73
	v_div_fixup_f32 v69, v70, v69, 1.0
	v_div_scale_f32 v70, s[2:3], v68, v68, 1.0
	v_rcp_f32_e32 v71, v70
	s_nop 0
	v_fma_f32 v72, -v70, v71, 1.0
	v_fmac_f32_e32 v71, v72, v71
	v_div_scale_f32 v72, vcc, 1.0, v68, 1.0
	v_mul_f32_e32 v73, v72, v71
	v_fma_f32 v74, -v70, v73, v72
	v_fmac_f32_e32 v73, v74, v71
	v_fma_f32 v70, -v70, v73, v72
	v_div_fmas_f32 v70, v70, v71, v73
	v_div_fixup_f32 v68, v70, v68, 1.0
	v_pk_fma_f32 v[116:117], v[30:31], v[68:69], v[116:117]
	s_waitcnt vmcnt(16)
	v_cvt_f32_f16_e32 v68, v206
	v_cvt_f32_f16_e32 v69, v207
	v_mul_f32_e32 v68, 0xbfb8aa3b, v68
	v_mul_f32_e32 v69, 0xbfb8aa3b, v69
	v_exp_f32_e32 v68, v68
	v_exp_f32_e32 v69, v69
	s_nop 0
	v_pk_add_f32 v[68:69], v[68:69], 1.0 op_sel_hi:[1,0]
	s_nop 0
	v_div_scale_f32 v70, s[2:3], v69, v69, 1.0
	v_rcp_f32_e32 v71, v70
	s_nop 0
	v_fma_f32 v72, -v70, v71, 1.0
	v_fmac_f32_e32 v71, v72, v71
	v_div_scale_f32 v72, vcc, 1.0, v69, 1.0
	v_mul_f32_e32 v73, v72, v71
	v_fma_f32 v74, -v70, v73, v72
	v_fmac_f32_e32 v73, v74, v71
	v_fma_f32 v70, -v70, v73, v72
	v_div_fmas_f32 v70, v70, v71, v73
	v_div_fixup_f32 v69, v70, v69, 1.0
	v_div_scale_f32 v70, s[2:3], v68, v68, 1.0
	v_rcp_f32_e32 v71, v70
	s_nop 0
	v_fma_f32 v72, -v70, v71, 1.0
	v_fmac_f32_e32 v71, v72, v71
	v_div_scale_f32 v72, vcc, 1.0, v68, 1.0
	v_mul_f32_e32 v73, v72, v71
	v_fma_f32 v74, -v70, v73, v72
	v_fmac_f32_e32 v73, v74, v71
	v_fma_f32 v70, -v70, v73, v72
	v_div_fmas_f32 v70, v70, v71, v73
	v_div_fixup_f32 v68, v70, v68, 1.0
	v_pk_fma_f32 v[114:115], v[32:33], v[68:69], v[114:115]
	s_waitcnt vmcnt(14)
	v_cvt_f32_f16_e32 v68, v208
	v_cvt_f32_f16_e32 v69, v209
	v_mul_f32_e32 v68, 0xbfb8aa3b, v68
	v_mul_f32_e32 v69, 0xbfb8aa3b, v69
	v_exp_f32_e32 v68, v68
	v_exp_f32_e32 v69, v69
	s_nop 0
	v_pk_add_f32 v[68:69], v[68:69], 1.0 op_sel_hi:[1,0]
	s_nop 0
	v_div_scale_f32 v70, s[2:3], v69, v69, 1.0
	v_rcp_f32_e32 v71, v70
	s_nop 0
	v_fma_f32 v72, -v70, v71, 1.0
	v_fmac_f32_e32 v71, v72, v71
	v_div_scale_f32 v72, vcc, 1.0, v69, 1.0
	v_mul_f32_e32 v73, v72, v71
	v_fma_f32 v74, -v70, v73, v72
	v_fmac_f32_e32 v73, v74, v71
	v_fma_f32 v70, -v70, v73, v72
	v_div_fmas_f32 v70, v70, v71, v73
	v_div_fixup_f32 v69, v70, v69, 1.0
	v_div_scale_f32 v70, s[2:3], v68, v68, 1.0
	v_rcp_f32_e32 v71, v70
	s_nop 0
	v_fma_f32 v72, -v70, v71, 1.0
	v_fmac_f32_e32 v71, v72, v71
	v_div_scale_f32 v72, vcc, 1.0, v68, 1.0
	v_mul_f32_e32 v73, v72, v71
	v_fma_f32 v74, -v70, v73, v72
	v_fmac_f32_e32 v73, v74, v71
	v_fma_f32 v70, -v70, v73, v72
	v_div_fmas_f32 v70, v70, v71, v73
	v_div_fixup_f32 v68, v70, v68, 1.0
	v_pk_fma_f32 v[112:113], v[2:3], v[68:69], v[112:113]
	s_waitcnt vmcnt(12)
	v_cvt_f32_f16_e32 v68, v210
	v_cvt_f32_f16_e32 v69, v211
	v_mul_f32_e32 v68, 0xbfb8aa3b, v68
	v_mul_f32_e32 v69, 0xbfb8aa3b, v69
	v_exp_f32_e32 v68, v68
	v_exp_f32_e32 v69, v69
	s_nop 0
	v_pk_add_f32 v[68:69], v[68:69], 1.0 op_sel_hi:[1,0]
	s_nop 0
	v_div_scale_f32 v70, s[2:3], v69, v69, 1.0
	v_rcp_f32_e32 v71, v70
	s_nop 0
	v_fma_f32 v72, -v70, v71, 1.0
	v_fmac_f32_e32 v71, v72, v71
	v_div_scale_f32 v72, vcc, 1.0, v69, 1.0
	v_mul_f32_e32 v73, v72, v71
	v_fma_f32 v74, -v70, v73, v72
	v_fmac_f32_e32 v73, v74, v71
	v_fma_f32 v70, -v70, v73, v72
	v_div_fmas_f32 v70, v70, v71, v73
	v_div_fixup_f32 v69, v70, v69, 1.0
	v_div_scale_f32 v70, s[2:3], v68, v68, 1.0
	v_rcp_f32_e32 v71, v70
	s_nop 0
	v_fma_f32 v72, -v70, v71, 1.0
	v_fmac_f32_e32 v71, v72, v71
	v_div_scale_f32 v72, vcc, 1.0, v68, 1.0
	v_mul_f32_e32 v73, v72, v71
	v_fma_f32 v74, -v70, v73, v72
	v_fmac_f32_e32 v73, v74, v71
	v_fma_f32 v70, -v70, v73, v72
	v_div_fmas_f32 v70, v70, v71, v73
	v_div_fixup_f32 v68, v70, v68, 1.0
	v_pk_fma_f32 v[110:111], v[4:5], v[68:69], v[110:111]
	s_waitcnt vmcnt(10)
	v_cvt_f32_f16_e32 v68, v212
	v_cvt_f32_f16_e32 v69, v213
	v_mul_f32_e32 v68, 0xbfb8aa3b, v68
	v_mul_f32_e32 v69, 0xbfb8aa3b, v69
	v_exp_f32_e32 v68, v68
	v_exp_f32_e32 v69, v69
	s_nop 0
	v_pk_add_f32 v[68:69], v[68:69], 1.0 op_sel_hi:[1,0]
	s_nop 0
	v_div_scale_f32 v70, s[2:3], v69, v69, 1.0
	v_rcp_f32_e32 v71, v70
	s_nop 0
	v_fma_f32 v72, -v70, v71, 1.0
	v_fmac_f32_e32 v71, v72, v71
	v_div_scale_f32 v72, vcc, 1.0, v69, 1.0
	v_mul_f32_e32 v73, v72, v71
	v_fma_f32 v74, -v70, v73, v72
	v_fmac_f32_e32 v73, v74, v71
	v_fma_f32 v70, -v70, v73, v72
	v_div_fmas_f32 v70, v70, v71, v73
	v_div_fixup_f32 v69, v70, v69, 1.0
	v_div_scale_f32 v70, s[2:3], v68, v68, 1.0
	v_rcp_f32_e32 v71, v70
	s_nop 0
	v_fma_f32 v72, -v70, v71, 1.0
	v_fmac_f32_e32 v71, v72, v71
	v_div_scale_f32 v72, vcc, 1.0, v68, 1.0
	v_mul_f32_e32 v73, v72, v71
	v_fma_f32 v74, -v70, v73, v72
	v_fmac_f32_e32 v73, v74, v71
	v_fma_f32 v70, -v70, v73, v72
	v_div_fmas_f32 v70, v70, v71, v73
	v_div_fixup_f32 v68, v70, v68, 1.0
	v_pk_fma_f32 v[108:109], v[6:7], v[68:69], v[108:109]
	s_waitcnt vmcnt(8)
;   __device__ __forceinline__ const float* x() const { return (const float*)(const __attribute__((address_space(1))) float*)kp[0]; }
; __device__ __forceinline__ float sigmoidf_(float x) { return 1.f / (1.f + __expf(-x)); }
; __device__ __forceinline__ void phase_merge(const KP& p, char* smem, int* q, int xcc) {
;     ...
;           [&](int mi, int ni, int r, int row, int col, float v) {
;             const float gz = (float)G[(size_t)row * NU + col];
;             tot[mi][ni][r] += sigmoidf_(gz) * v;
;           },
	v_cvt_f32_f16_e32 v68, v214
	v_cvt_f32_f16_e32 v69, v215
	v_mul_f32_e32 v68, 0xbfb8aa3b, v68
	v_mul_f32_e32 v69, 0xbfb8aa3b, v69
	v_exp_f32_e32 v68, v68
	v_exp_f32_e32 v69, v69
	s_nop 0
	v_pk_add_f32 v[68:69], v[68:69], 1.0 op_sel_hi:[1,0]
	s_nop 0
	v_div_scale_f32 v70, s[2:3], v69, v69, 1.0
	v_rcp_f32_e32 v71, v70
	s_nop 0
	v_fma_f32 v72, -v70, v71, 1.0
	v_fmac_f32_e32 v71, v72, v71
	v_div_scale_f32 v72, vcc, 1.0, v69, 1.0
	v_mul_f32_e32 v73, v72, v71
	v_fma_f32 v74, -v70, v73, v72
	v_fmac_f32_e32 v73, v74, v71
	v_fma_f32 v70, -v70, v73, v72
	v_div_fmas_f32 v70, v70, v71, v73
	v_div_fixup_f32 v69, v70, v69, 1.0
	v_div_scale_f32 v70, s[2:3], v68, v68, 1.0
	v_rcp_f32_e32 v71, v70
	s_nop 0
	v_fma_f32 v72, -v70, v71, 1.0
	v_fmac_f32_e32 v71, v72, v71
	v_div_scale_f32 v72, vcc, 1.0, v68, 1.0
	v_mul_f32_e32 v73, v72, v71
	v_fma_f32 v74, -v70, v73, v72
	v_fmac_f32_e32 v73, v74, v71
	v_fma_f32 v70, -v70, v73, v72
	v_div_fmas_f32 v70, v70, v71, v73
	v_div_fixup_f32 v68, v70, v68, 1.0
	v_pk_fma_f32 v[106:107], v[8:9], v[68:69], v[106:107]
	s_waitcnt vmcnt(6)
	v_cvt_f32_f16_e32 v68, v216
	v_cvt_f32_f16_e32 v69, v217
	v_mul_f32_e32 v68, 0xbfb8aa3b, v68
	v_mul_f32_e32 v69, 0xbfb8aa3b, v69
	v_exp_f32_e32 v68, v68
	v_exp_f32_e32 v69, v69
	s_nop 0
	v_pk_add_f32 v[68:69], v[68:69], 1.0 op_sel_hi:[1,0]
	s_nop 0
	v_div_scale_f32 v70, s[2:3], v69, v69, 1.0
	v_rcp_f32_e32 v71, v70
	s_nop 0
	v_fma_f32 v72, -v70, v71, 1.0
	v_fmac_f32_e32 v71, v72, v71
	v_div_scale_f32 v72, vcc, 1.0, v69, 1.0
	v_mul_f32_e32 v73, v72, v71
	v_fma_f32 v74, -v70, v73, v72
	v_fmac_f32_e32 v73, v74, v71
	v_fma_f32 v70, -v70, v73, v72
	v_div_fmas_f32 v70, v70, v71, v73
	v_div_fixup_f32 v69, v70, v69, 1.0
	v_div_scale_f32 v70, s[2:3], v68, v68, 1.0
	v_rcp_f32_e32 v71, v70
	s_nop 0
	v_fma_f32 v72, -v70, v71, 1.0
	v_fmac_f32_e32 v71, v72, v71
	v_div_scale_f32 v72, vcc, 1.0, v68, 1.0
	v_mul_f32_e32 v73, v72, v71
	v_fma_f32 v74, -v70, v73, v72
	v_fmac_f32_e32 v73, v74, v71
	v_fma_f32 v70, -v70, v73, v72
	v_div_fmas_f32 v70, v70, v71, v73
	v_div_fixup_f32 v68, v70, v68, 1.0
	v_pk_fma_f32 v[104:105], v[10:11], v[68:69], v[104:105]
	s_waitcnt vmcnt(4)
	v_cvt_f32_f16_e32 v68, v218
	v_cvt_f32_f16_e32 v69, v219
	v_mul_f32_e32 v68, 0xbfb8aa3b, v68
	v_mul_f32_e32 v69, 0xbfb8aa3b, v69
	v_exp_f32_e32 v68, v68
	v_exp_f32_e32 v69, v69
	s_nop 0
	v_pk_add_f32 v[68:69], v[68:69], 1.0 op_sel_hi:[1,0]
	s_nop 0
	v_div_scale_f32 v70, s[2:3], v69, v69, 1.0
	v_rcp_f32_e32 v71, v70
	s_nop 0
	v_fma_f32 v72, -v70, v71, 1.0
	v_fmac_f32_e32 v71, v72, v71
	v_div_scale_f32 v72, vcc, 1.0, v69, 1.0
	v_mul_f32_e32 v73, v72, v71
	v_fma_f32 v74, -v70, v73, v72
	v_fmac_f32_e32 v73, v74, v71
	v_fma_f32 v70, -v70, v73, v72
	v_div_fmas_f32 v70, v70, v71, v73
	v_div_fixup_f32 v69, v70, v69, 1.0
	v_div_scale_f32 v70, s[2:3], v68, v68, 1.0
	v_rcp_f32_e32 v71, v70
	s_nop 0
	v_fma_f32 v72, -v70, v71, 1.0
	v_fmac_f32_e32 v71, v72, v71
	v_div_scale_f32 v72, vcc, 1.0, v68, 1.0
	v_mul_f32_e32 v73, v72, v71
	v_fma_f32 v74, -v70, v73, v72
	v_fmac_f32_e32 v73, v74, v71
	v_fma_f32 v70, -v70, v73, v72
	v_div_fmas_f32 v70, v70, v71, v73
	v_div_fixup_f32 v68, v70, v68, 1.0
	v_pk_fma_f32 v[102:103], v[12:13], v[68:69], v[102:103]
	s_waitcnt vmcnt(2)
	v_cvt_f32_f16_e32 v68, v220
	v_cvt_f32_f16_e32 v69, v221
	v_mul_f32_e32 v68, 0xbfb8aa3b, v68
	v_mul_f32_e32 v69, 0xbfb8aa3b, v69
	v_exp_f32_e32 v68, v68
	v_exp_f32_e32 v69, v69
	s_nop 0
	v_pk_add_f32 v[68:69], v[68:69], 1.0 op_sel_hi:[1,0]
	s_nop 0
	v_div_scale_f32 v70, s[2:3], v69, v69, 1.0
	v_rcp_f32_e32 v71, v70
	s_nop 0
	v_fma_f32 v72, -v70, v71, 1.0
	v_fmac_f32_e32 v71, v72, v71
	v_div_scale_f32 v72, vcc, 1.0, v69, 1.0
	v_mul_f32_e32 v73, v72, v71
	v_fma_f32 v74, -v70, v73, v72
	v_fmac_f32_e32 v73, v74, v71
	v_fma_f32 v70, -v70, v73, v72
	v_div_fmas_f32 v70, v70, v71, v73
	v_div_fixup_f32 v69, v70, v69, 1.0
	v_div_scale_f32 v70, s[2:3], v68, v68, 1.0
	v_rcp_f32_e32 v71, v70
	s_nop 0
	v_fma_f32 v72, -v70, v71, 1.0
	v_fmac_f32_e32 v71, v72, v71
	v_div_scale_f32 v72, vcc, 1.0, v68, 1.0
	v_mul_f32_e32 v73, v72, v71
	v_fma_f32 v74, -v70, v73, v72
	v_fmac_f32_e32 v73, v74, v71
	v_fma_f32 v70, -v70, v73, v72
	v_div_fmas_f32 v70, v70, v71, v73
	v_div_fixup_f32 v68, v70, v68, 1.0
	v_pk_fma_f32 v[100:101], v[14:15], v[68:69], v[100:101]
	s_waitcnt vmcnt(0)
	v_cvt_f32_f16_e32 v68, v222
	v_cvt_f32_f16_e32 v69, v223
	v_mul_f32_e32 v68, 0xbfb8aa3b, v68
	v_mul_f32_e32 v69, 0xbfb8aa3b, v69
	v_exp_f32_e32 v68, v68
	v_exp_f32_e32 v69, v69
	s_nop 0
	v_pk_add_f32 v[68:69], v[68:69], 1.0 op_sel_hi:[1,0]
	s_nop 0
	v_div_scale_f32 v70, s[2:3], v69, v69, 1.0
	v_rcp_f32_e32 v71, v70
	s_nop 0
	v_fma_f32 v72, -v70, v71, 1.0
	v_fmac_f32_e32 v71, v72, v71
	v_div_scale_f32 v72, vcc, 1.0, v69, 1.0
	v_mul_f32_e32 v73, v72, v71
	v_fma_f32 v74, -v70, v73, v72
	v_fmac_f32_e32 v73, v74, v71
	v_fma_f32 v70, -v70, v73, v72
	v_div_fmas_f32 v70, v70, v71, v73
	v_div_fixup_f32 v69, v70, v69, 1.0
	v_div_scale_f32 v70, s[2:3], v68, v68, 1.0
	v_rcp_f32_e32 v71, v70
	s_nop 0
	v_fma_f32 v72, -v70, v71, 1.0
	v_fmac_f32_e32 v71, v72, v71
	v_div_scale_f32 v72, vcc, 1.0, v68, 1.0
	v_mul_f32_e32 v73, v72, v71
	v_fma_f32 v74, -v70, v73, v72
	v_fmac_f32_e32 v73, v74, v71
	v_fma_f32 v70, -v70, v73, v72
	v_div_fmas_f32 v70, v70, v71, v73
	v_div_fixup_f32 v68, v70, v68, 1.0
	v_pk_fma_f32 v[98:99], v[16:17], v[68:69], v[98:99]
	s_cmp_lg_u32 s56, 3
	s_cbranch_scc1 .LBB0_1742
;   __device__ __forceinline__ const float* x() const { return (const float*)(const __attribute__((address_space(1))) float*)kp[0]; }
;   __device__ __forceinline__ half_t* mm() const { return (half_t*)(ws() + OFF_mm); }
; __device__ __forceinline__ void phase_merge(const KP& p, char* smem, int* q, int xcc) {
;     ...
;     int tidx = threadIdx.x;
;     asm volatile("" : "+v"(tidx));
;     const int lane = tidx & 63, wid = tidx >> 6, wm = wid >> 1, wn = wid & 1;
; #pragma unroll
;     for (int mi = 0; mi < 2; ++mi)
; #pragma unroll
;       for (int ni = 0; ni < 2; ++ni)
; #pragma unroll
;         for (int r = 0; r < 16; ++r) {
;           const int row = wm * 64 + mi * 32 + (r & 3) + 8 * (r >> 2) + 4 * (lane >> 5);
;           const int col = wn * 64 + ni * 32 + (lane & 31);
;           p.mm()[(size_t)(m0 + row) * DM + n0 + col] = (half_t)tot[mi][ni][r];
;         }
	v_mov_b32_e32 v0, v224
	v_ashrrev_i32_e32 v2, 1, v0
	v_and_b32_e32 v2, 0xffffffc0, v2
	v_lshrrev_b32_e32 v3, 3, v0
	v_add_u32_e32 v2, s14, v2
	v_and_or_b32 v2, v3, 4, v2
	v_and_b32_e32 v3, 31, v0
	v_bfe_u32 v4, v0, 6, 1
	v_lshlrev_b32_e32 v3, 1, v3
	v_lshl_or_b32 v3, v4, 21, v3
	v_lshl_add_u32 v4, v2, 6, v3
	s_lshr_b32 s2, s18, 6
	s_lshl_b32 s2, s2, 20
	s_add_u32 s2, s44, s2
	s_addc_u32 s3, s45, 0
	s_add_u32 s40, s2, 0x100000
	s_addc_u32 s41, s3, 0
	v_cvt_f16_f32_e32 v5, v160
	global_store_short v4, v5, s[2:3]
	v_cvt_f16_f32_e32 v6, v161
	global_store_short v4, v6, s[2:3] offset:64
	v_cvt_f16_f32_e32 v7, v158
	global_store_short v4, v7, s[2:3] offset:128
	v_cvt_f16_f32_e32 v8, v159
	global_store_short v4, v8, s[2:3] offset:192
	v_cvt_f16_f32_e32 v9, v156
	global_store_short v4, v9, s[2:3] offset:512
	v_cvt_f16_f32_e32 v10, v157
	global_store_short v4, v10, s[2:3] offset:576
	v_cvt_f16_f32_e32 v11, v154
	global_store_short v4, v11, s[2:3] offset:640
	v_cvt_f16_f32_e32 v12, v155
	global_store_short v4, v12, s[2:3] offset:704
	v_cvt_f16_f32_e32 v5, v152
	global_store_short v4, v5, s[2:3] offset:1024
	v_cvt_f16_f32_e32 v6, v153
	global_store_short v4, v6, s[2:3] offset:1088
	v_cvt_f16_f32_e32 v7, v150
	global_store_short v4, v7, s[2:3] offset:1152
	v_cvt_f16_f32_e32 v8, v151
	global_store_short v4, v8, s[2:3] offset:1216
	v_cvt_f16_f32_e32 v9, v148
	global_store_short v4, v9, s[2:3] offset:1536
	v_cvt_f16_f32_e32 v10, v149
	global_store_short v4, v10, s[2:3] offset:1600
	v_cvt_f16_f32_e32 v11, v146
	global_store_short v4, v11, s[2:3] offset:1664
	v_cvt_f16_f32_e32 v12, v147
	global_store_short v4, v12, s[2:3] offset:1728
	v_cvt_f16_f32_e32 v5, v144
	global_store_short v4, v5, s[40:41]
	v_cvt_f16_f32_e32 v6, v145
	global_store_short v4, v6, s[40:41] offset:64
	v_cvt_f16_f32_e32 v7, v142
	global_store_short v4, v7, s[40:41] offset:128
	v_cvt_f16_f32_e32 v8, v143
	global_store_short v4, v8, s[40:41] offset:192
	v_cvt_f16_f32_e32 v9, v140
	global_store_short v4, v9, s[40:41] offset:512
	v_cvt_f16_f32_e32 v10, v141
	global_store_short v4, v10, s[40:41] offset:576
	v_cvt_f16_f32_e32 v11, v138
	global_store_short v4, v11, s[40:41] offset:640
	v_cvt_f16_f32_e32 v12, v139
	global_store_short v4, v12, s[40:41] offset:704
	v_cvt_f16_f32_e32 v5, v136
	global_store_short v4, v5, s[40:41] offset:1024
	v_cvt_f16_f32_e32 v6, v137
	global_store_short v4, v6, s[40:41] offset:1088
	v_cvt_f16_f32_e32 v7, v134
	global_store_short v4, v7, s[40:41] offset:1152
	v_cvt_f16_f32_e32 v8, v135
	global_store_short v4, v8, s[40:41] offset:1216
	v_cvt_f16_f32_e32 v9, v132
	global_store_short v4, v9, s[40:41] offset:1536
	v_cvt_f16_f32_e32 v10, v133
	global_store_short v4, v10, s[40:41] offset:1600
	v_cvt_f16_f32_e32 v11, v130
	global_store_short v4, v11, s[40:41] offset:1664
	v_cvt_f16_f32_e32 v12, v131
	global_store_short v4, v12, s[40:41] offset:1728
	v_cvt_f16_f32_e32 v5, v128
	global_store_short v4, v5, s[2:3] offset:2048
	v_cvt_f16_f32_e32 v6, v129
	global_store_short v4, v6, s[2:3] offset:2112
	v_cvt_f16_f32_e32 v7, v126
	global_store_short v4, v7, s[2:3] offset:2176
	v_cvt_f16_f32_e32 v8, v127
	global_store_short v4, v8, s[2:3] offset:2240
	v_cvt_f16_f32_e32 v9, v124
	global_store_short v4, v9, s[2:3] offset:2560
	v_cvt_f16_f32_e32 v10, v125
	global_store_short v4, v10, s[2:3] offset:2624
	v_cvt_f16_f32_e32 v11, v122
	global_store_short v4, v11, s[2:3] offset:2688
	v_cvt_f16_f32_e32 v12, v123
	global_store_short v4, v12, s[2:3] offset:2752
	v_cvt_f16_f32_e32 v5, v120
	global_store_short v4, v5, s[2:3] offset:3072
	v_cvt_f16_f32_e32 v6, v121
	global_store_short v4, v6, s[2:3] offset:3136
	v_cvt_f16_f32_e32 v7, v118
	global_store_short v4, v7, s[2:3] offset:3200
	v_cvt_f16_f32_e32 v8, v119
	global_store_short v4, v8, s[2:3] offset:3264
	v_cvt_f16_f32_e32 v9, v116
	global_store_short v4, v9, s[2:3] offset:3584
	v_cvt_f16_f32_e32 v10, v117
	global_store_short v4, v10, s[2:3] offset:3648
	v_cvt_f16_f32_e32 v11, v114
	global_store_short v4, v11, s[2:3] offset:3712
	v_cvt_f16_f32_e32 v12, v115
	global_store_short v4, v12, s[2:3] offset:3776
	v_cvt_f16_f32_e32 v5, v112
	global_store_short v4, v5, s[40:41] offset:2048
	v_cvt_f16_f32_e32 v6, v113
	global_store_short v4, v6, s[40:41] offset:2112
	v_cvt_f16_f32_e32 v7, v110
	global_store_short v4, v7, s[40:41] offset:2176
	v_cvt_f16_f32_e32 v8, v111
	global_store_short v4, v8, s[40:41] offset:2240
	v_cvt_f16_f32_e32 v9, v108
	global_store_short v4, v9, s[40:41] offset:2560
	v_cvt_f16_f32_e32 v10, v109
	global_store_short v4, v10, s[40:41] offset:2624
	v_cvt_f16_f32_e32 v11, v106
	global_store_short v4, v11, s[40:41] offset:2688
	v_cvt_f16_f32_e32 v12, v107
	global_store_short v4, v12, s[40:41] offset:2752
	v_cvt_f16_f32_e32 v5, v104
	global_store_short v4, v5, s[40:41] offset:3072
	v_cvt_f16_f32_e32 v6, v105
	global_store_short v4, v6, s[40:41] offset:3136
	v_cvt_f16_f32_e32 v7, v102
	global_store_short v4, v7, s[40:41] offset:3200
	v_cvt_f16_f32_e32 v8, v103
	global_store_short v4, v8, s[40:41] offset:3264
	v_cvt_f16_f32_e32 v9, v100
	global_store_short v4, v9, s[40:41] offset:3584
	v_cvt_f16_f32_e32 v10, v101
	global_store_short v4, v10, s[40:41] offset:3648
	v_cvt_f16_f32_e32 v11, v98
	global_store_short v4, v11, s[40:41] offset:3712
	v_cvt_f16_f32_e32 v12, v99
	global_store_short v4, v12, s[40:41] offset:3776
	s_branch .LBB0_1731
